# speedup vs baseline: 1.0043x; 1.0043x over previous
.LBB0_1405:
	s_ashr_i32 s21, s20, 31
	s_lshl_b64 s[20:21], s[20:21], 19
	s_add_u32 s2, s28, s20
	s_addc_u32 s25, s29, s21
	s_lshl_b32 s40, s39, 8
	s_ashr_i32 s41, s40, 31
	s_lshl_b64 s[22:23], s[40:41], 1
	s_add_u32 s24, s2, s22
	s_addc_u32 s25, s25, s23
	s_add_u32 s2, s92, s20
	s_addc_u32 s20, s93, s21
	s_add_u32 s22, s2, s22
	s_addc_u32 s23, s20, s23
	v_readlane_b32 s20, v255, 15
	v_readlane_b32 s21, v255, 16
	s_load_dwordx2 s[20:21], s[20:21], 0x90
	v_lshlrev_b32_e32 v132, 2, v188
	v_lshl_add_u64 v[130:131], s[24:25], 0, v[196:197]
	v_lshlrev_b32_e32 v0, 1, v188
	v_lshl_add_u64 v[130:131], v[130:131], 0, v[0:1]
	s_waitcnt lgkmcnt(0)
	s_add_u32 s2, s20, s34
	s_addc_u32 s39, s21, 0
	s_lshl_b64 s[20:21], s[40:41], 2
	s_add_u32 s20, s2, s20
	s_addc_u32 s21, s39, s21
	v_and_b32_e32 v176, 63, v182
	v_and_b32_e32 v174, 0x300, v132
	v_lshl_add_u32 v174, v176, 2, v174
	global_load_dword v175, v174, s[20:21]
	v_lshrrev_b32_e32 v173, 6, v182
	v_lshlrev_b32_e32 v173, 9, v173
	v_add_u32_e32 v173, 0x10000, v173
	v_and_b32_e32 v172, 48, v132
	v_add_u32_e32 v172, v173, v172
	v_lshl_add_u32 v173, v176, 2, v173
	v_bfe_u32 v176, v182, 4, 1
	v_mul_u32_u24_e32 v176, 24, v176
	v_mov_b32_e32 v177, 0
	v_mov_b64_e32 v[170:171], v[130:131]
	global_load_dwordx2 v[142:143], v[170:171], off
	global_load_dwordx2 v[144:145], v[170:171], off offset:32
	global_load_dwordx2 v[146:147], v[170:171], off offset:64
	global_load_dwordx2 v[148:149], v[170:171], off offset:96
	v_add_co_u32_e32 v170, vcc, 0x8000, v170
	s_nop 1
	v_addc_co_u32_e32 v171, vcc, 0, v171, vcc
	global_load_dwordx2 v[150:151], v[170:171], off
	global_load_dwordx2 v[152:153], v[170:171], off offset:32
	global_load_dwordx2 v[154:155], v[170:171], off offset:64
	global_load_dwordx2 v[156:157], v[170:171], off offset:96
	v_add_co_u32_e32 v170, vcc, 0x8000, v170
	s_nop 1
	v_addc_co_u32_e32 v171, vcc, 0, v171, vcc
	global_load_dwordx2 v[158:159], v[170:171], off
	global_load_dwordx2 v[160:161], v[170:171], off offset:32
	global_load_dwordx2 v[162:163], v[170:171], off offset:64
	global_load_dwordx2 v[164:165], v[170:171], off offset:96
	v_add_co_u32_e32 v170, vcc, 0x8000, v170
	s_nop 1
	v_addc_co_u32_e32 v171, vcc, 0, v171, vcc
	global_load_dwordx2 v[166:167], v[170:171], off
	global_load_dwordx2 v[168:169], v[170:171], off offset:32
	s_waitcnt vmcnt(14)
	ds_write_b32 v173, v175
	s_waitcnt lgkmcnt(0)
	ds_read_b128 v[134:137], v172
	s_waitcnt vmcnt(13)
	v_mov_b64_e32 v[138:139], v[142:143]
	global_load_dwordx2 v[142:143], v[170:171], off offset:64
	s_waitcnt lgkmcnt(0)
	v_add_f32_e32 v126, v126, v134
	v_add_f32_e32 v127, v127, v135
	v_mul_f32_e32 v126, 0xbfb8aa3b, v126
	v_mul_f32_e32 v127, 0xbfb8aa3b, v127
	v_exp_f32_e32 v126, v126
	v_exp_f32_e32 v127, v127
	v_lshlrev_b32_e32 v133, 16, v138
	v_and_b32_e32 v138, 0xffff0000, v138
	v_add_f32_e32 v126, 1.0, v126
	v_add_f32_e32 v127, 1.0, v127
	v_rcp_f32_e32 v126, v126
	v_rcp_f32_e32 v127, v127
	v_lshlrev_b32_e32 v140, 16, v139
	v_and_b32_e32 v139, 0xffff0000, v139
	v_mul_f32_e32 v126, v126, v133
	v_mul_f32_e32 v127, v127, v138
	v_cvt_pk_bf16_f32 v248, v126, v127
	v_add_f32_e32 v126, v128, v136
	v_add_f32_e32 v127, v129, v137
	v_mul_f32_e32 v126, 0xbfb8aa3b, v126
	v_mul_f32_e32 v127, 0xbfb8aa3b, v127
	v_exp_f32_e32 v126, v126
	v_exp_f32_e32 v127, v127
	v_add_f32_e32 v126, 1.0, v126
	v_add_f32_e32 v127, 1.0, v127
	v_rcp_f32_e32 v126, v126
	v_rcp_f32_e32 v127, v127
	v_mul_f32_e32 v126, v126, v140
	v_mul_f32_e32 v127, v127, v139
	v_cvt_pk_bf16_f32 v249, v126, v127
	v_lshl_add_u64 v[126:127], s[22:23], 0, v[196:197]
	v_lshl_add_u64 v[126:127], v[126:127], 0, v[0:1]
	s_waitcnt vmcnt(13)
	v_mov_b64_e32 v[128:129], v[144:145]
	global_load_dwordx2 v[144:145], v[170:171], off offset:96
	v_add_co_u32_e32 v170, vcc, 0x8000, v170
	s_nop 1
	v_addc_co_u32_e32 v171, vcc, 0, v171, vcc
	ds_read_b128 v[134:137], v172 offset:64
	v_lshlrev_b32_e32 v133, 16, v128
	s_waitcnt lgkmcnt(0)
	v_add_f32_e32 v122, v122, v134
	v_add_f32_e32 v123, v123, v135
	v_mul_f32_e32 v122, 0xbfb8aa3b, v122
	v_mul_f32_e32 v123, 0xbfb8aa3b, v123
	v_exp_f32_e32 v122, v122
	v_exp_f32_e32 v123, v123
	v_and_b32_e32 v128, 0xffff0000, v128
	v_lshlrev_b32_e32 v138, 16, v129
	v_add_f32_e32 v122, 1.0, v122
	v_add_f32_e32 v123, 1.0, v123
	v_rcp_f32_e32 v122, v122
	v_rcp_f32_e32 v123, v123
	v_and_b32_e32 v129, 0xffff0000, v129
	v_mul_f32_e32 v122, v122, v133
	v_mul_f32_e32 v123, v123, v128
	v_cvt_pk_bf16_f32 v250, v122, v123
	v_add_f32_e32 v123, v124, v136
	v_mul_f32_e32 v123, 0xbfb8aa3b, v123
	v_add_f32_e32 v124, v125, v137
	v_exp_f32_e32 v123, v123
	v_mul_f32_e32 v124, 0xbfb8aa3b, v124
	v_exp_f32_e32 v124, v124
	v_add_f32_e32 v123, 1.0, v123
	v_rcp_f32_e32 v123, v123
	v_add_f32_e32 v124, 1.0, v124
	v_rcp_f32_e32 v124, v124
	v_mul_f32_e32 v123, v123, v138
	v_mul_f32_e32 v124, v124, v129
	v_cvt_pk_bf16_f32 v251, v123, v124
	v_lshl_add_u64 v[252:253], v[126:127], 0, v[176:177]
	s_nop 1
	v_permlane16_swap_b32_e32 v248, v250
	v_permlane16_swap_b32_e32 v249, v251
	global_store_dwordx4 v[252:253], v[248:251], off
	s_waitcnt vmcnt(14)
	v_mov_b64_e32 v[128:129], v[146:147]
	global_load_dwordx2 v[146:147], v[170:171], off
	ds_read_b128 v[122:125], v172 offset:128
	v_lshlrev_b32_e32 v133, 16, v128
	s_waitcnt lgkmcnt(0)
	v_add_f32_e32 v118, v118, v122
	v_add_f32_e32 v119, v119, v123
	v_mul_f32_e32 v118, 0xbfb8aa3b, v118
	v_mul_f32_e32 v119, 0xbfb8aa3b, v119
	v_exp_f32_e32 v118, v118
	v_exp_f32_e32 v119, v119
	v_and_b32_e32 v128, 0xffff0000, v128
	v_lshlrev_b32_e32 v134, 16, v129
	v_add_f32_e32 v118, 1.0, v118
	v_add_f32_e32 v119, 1.0, v119
	v_rcp_f32_e32 v118, v118
	v_rcp_f32_e32 v119, v119
	v_and_b32_e32 v129, 0xffff0000, v129
	v_mul_f32_e32 v118, v118, v133
	v_mul_f32_e32 v119, v119, v128
	v_cvt_pk_bf16_f32 v248, v118, v119
	v_add_f32_e32 v119, v120, v124
	v_mul_f32_e32 v119, 0xbfb8aa3b, v119
	v_add_f32_e32 v120, v121, v125
	v_exp_f32_e32 v119, v119
	v_mul_f32_e32 v120, 0xbfb8aa3b, v120
	v_exp_f32_e32 v120, v120
	v_add_f32_e32 v119, 1.0, v119
	v_rcp_f32_e32 v119, v119
	v_add_f32_e32 v120, 1.0, v120
	v_rcp_f32_e32 v120, v120
	v_mul_f32_e32 v119, v119, v134
	v_mul_f32_e32 v120, v120, v129
	v_cvt_pk_bf16_f32 v249, v119, v120
	s_waitcnt vmcnt(14)
	v_mov_b64_e32 v[118:119], v[148:149]
	global_load_dwordx2 v[148:149], v[170:171], off offset:32
	ds_read_b128 v[120:123], v172 offset:192
	v_lshlrev_b32_e32 v124, 16, v118
	s_waitcnt lgkmcnt(0)
	v_add_f32_e32 v114, v114, v120
	v_add_f32_e32 v115, v115, v121
	v_mul_f32_e32 v114, 0xbfb8aa3b, v114
	v_mul_f32_e32 v115, 0xbfb8aa3b, v115
	v_exp_f32_e32 v114, v114
	v_exp_f32_e32 v115, v115
	v_and_b32_e32 v118, 0xffff0000, v118
	v_lshlrev_b32_e32 v125, 16, v119
	v_add_f32_e32 v114, 1.0, v114
	v_add_f32_e32 v115, 1.0, v115
	v_rcp_f32_e32 v114, v114
	v_rcp_f32_e32 v115, v115
	v_and_b32_e32 v119, 0xffff0000, v119
	v_mul_f32_e32 v114, v114, v124
	v_mul_f32_e32 v115, v115, v118
	v_cvt_pk_bf16_f32 v250, v114, v115
	v_add_f32_e32 v115, v116, v122
	v_mul_f32_e32 v115, 0xbfb8aa3b, v115
	v_add_f32_e32 v116, v117, v123
	v_exp_f32_e32 v115, v115
	v_mul_f32_e32 v116, 0xbfb8aa3b, v116
	v_exp_f32_e32 v116, v116
	v_add_f32_e32 v115, 1.0, v115
	v_rcp_f32_e32 v115, v115
	v_add_f32_e32 v116, 1.0, v116
	v_rcp_f32_e32 v116, v116
	v_mul_f32_e32 v115, v115, v125
	v_mul_f32_e32 v116, v116, v119
	v_cvt_pk_bf16_f32 v251, v115, v116
	v_lshl_add_u64 v[252:253], v[126:127], 0, v[176:177]
	s_nop 1
	v_permlane16_swap_b32_e32 v248, v250
	v_permlane16_swap_b32_e32 v249, v251
	global_store_dwordx4 v[252:253], v[248:251], off offset:64
	v_lshl_add_u64 v[114:115], s[24:25], 0, v[198:199]
	v_lshl_add_u64 v[114:115], v[114:115], 0, v[0:1]
	s_waitcnt vmcnt(15)
	v_mov_b64_e32 v[120:121], v[150:151]
	global_load_dwordx2 v[150:151], v[170:171], off offset:64
	ds_read_b128 v[116:119], v172
	v_lshlrev_b32_e32 v122, 16, v120
	s_waitcnt lgkmcnt(0)
	v_add_f32_e32 v110, v110, v116
	v_add_f32_e32 v111, v111, v117
	v_mul_f32_e32 v110, 0xbfb8aa3b, v110
	v_mul_f32_e32 v111, 0xbfb8aa3b, v111
	v_exp_f32_e32 v110, v110
	v_exp_f32_e32 v111, v111
	v_and_b32_e32 v120, 0xffff0000, v120
	v_lshlrev_b32_e32 v123, 16, v121
	v_add_f32_e32 v110, 1.0, v110
	v_add_f32_e32 v111, 1.0, v111
	v_rcp_f32_e32 v110, v110
	v_rcp_f32_e32 v111, v111
	v_and_b32_e32 v121, 0xffff0000, v121
	v_mul_f32_e32 v110, v110, v122
	v_mul_f32_e32 v111, v111, v120
	v_cvt_pk_bf16_f32 v248, v110, v111
	v_add_f32_e32 v110, v112, v118
	v_add_f32_e32 v111, v113, v119
	v_mul_f32_e32 v110, 0xbfb8aa3b, v110
	v_mul_f32_e32 v111, 0xbfb8aa3b, v111
	v_exp_f32_e32 v110, v110
	v_exp_f32_e32 v111, v111
	v_add_f32_e32 v110, 1.0, v110
	v_add_f32_e32 v111, 1.0, v111
	v_rcp_f32_e32 v110, v110
	v_rcp_f32_e32 v111, v111
	v_mul_f32_e32 v110, v110, v123
	v_mul_f32_e32 v111, v111, v121
	v_cvt_pk_bf16_f32 v249, v110, v111
	v_lshl_add_u64 v[110:111], s[22:23], 0, v[198:199]
	v_lshl_add_u64 v[110:111], v[110:111], 0, v[0:1]
	s_waitcnt vmcnt(15)
	v_mov_b64_e32 v[112:113], v[152:153]
	global_load_dwordx2 v[152:153], v[170:171], off offset:96
	v_add_co_u32_e32 v170, vcc, 0x8000, v170
	s_nop 1
	v_addc_co_u32_e32 v171, vcc, 0, v171, vcc
	ds_read_b128 v[116:119], v172 offset:64
	v_lshlrev_b32_e32 v120, 16, v112
	s_waitcnt lgkmcnt(0)
	v_add_f32_e32 v106, v106, v116
	v_add_f32_e32 v107, v107, v117
	v_mul_f32_e32 v106, 0xbfb8aa3b, v106
	v_mul_f32_e32 v107, 0xbfb8aa3b, v107
	v_exp_f32_e32 v106, v106
	v_exp_f32_e32 v107, v107
	v_and_b32_e32 v112, 0xffff0000, v112
	v_lshlrev_b32_e32 v121, 16, v113
	v_add_f32_e32 v106, 1.0, v106
	v_add_f32_e32 v107, 1.0, v107
	v_rcp_f32_e32 v106, v106
	v_rcp_f32_e32 v107, v107
	v_and_b32_e32 v113, 0xffff0000, v113
	v_mul_f32_e32 v106, v106, v120
	v_mul_f32_e32 v107, v107, v112
	v_cvt_pk_bf16_f32 v250, v106, v107
	v_add_f32_e32 v107, v108, v118
	v_mul_f32_e32 v107, 0xbfb8aa3b, v107
	v_add_f32_e32 v108, v109, v119
	v_exp_f32_e32 v107, v107
	v_mul_f32_e32 v108, 0xbfb8aa3b, v108
	v_exp_f32_e32 v108, v108
	v_add_f32_e32 v107, 1.0, v107
	v_rcp_f32_e32 v107, v107
	v_add_f32_e32 v108, 1.0, v108
	v_rcp_f32_e32 v108, v108
	v_mul_f32_e32 v107, v107, v121
	v_mul_f32_e32 v108, v108, v113
	v_cvt_pk_bf16_f32 v251, v107, v108
	v_lshl_add_u64 v[252:253], v[110:111], 0, v[176:177]
	s_nop 1
	v_permlane16_swap_b32_e32 v248, v250
	v_permlane16_swap_b32_e32 v249, v251
	global_store_dwordx4 v[252:253], v[248:251], off
	s_waitcnt vmcnt(16)
	v_mov_b64_e32 v[112:113], v[154:155]
	global_load_dwordx2 v[154:155], v[170:171], off
	ds_read_b128 v[106:109], v172 offset:128
	v_lshlrev_b32_e32 v116, 16, v112
	s_waitcnt lgkmcnt(0)
	v_add_f32_e32 v102, v102, v106
	v_add_f32_e32 v103, v103, v107
	v_mul_f32_e32 v102, 0xbfb8aa3b, v102
	v_mul_f32_e32 v103, 0xbfb8aa3b, v103
	v_exp_f32_e32 v102, v102
	v_exp_f32_e32 v103, v103
	v_and_b32_e32 v112, 0xffff0000, v112
	v_lshlrev_b32_e32 v117, 16, v113
	v_add_f32_e32 v102, 1.0, v102
	v_add_f32_e32 v103, 1.0, v103
	v_rcp_f32_e32 v102, v102
	v_rcp_f32_e32 v103, v103
	v_and_b32_e32 v113, 0xffff0000, v113
	v_mul_f32_e32 v102, v102, v116
	v_mul_f32_e32 v103, v103, v112
	v_cvt_pk_bf16_f32 v248, v102, v103
	v_add_f32_e32 v103, v104, v108
	v_mul_f32_e32 v103, 0xbfb8aa3b, v103
	v_add_f32_e32 v104, v105, v109
	v_exp_f32_e32 v103, v103
	v_mul_f32_e32 v104, 0xbfb8aa3b, v104
	v_exp_f32_e32 v104, v104
	v_add_f32_e32 v103, 1.0, v103
	v_rcp_f32_e32 v103, v103
	v_add_f32_e32 v104, 1.0, v104
	v_rcp_f32_e32 v104, v104
	v_mul_f32_e32 v103, v103, v117
	v_mul_f32_e32 v104, v104, v113
	v_cvt_pk_bf16_f32 v249, v103, v104
	s_waitcnt vmcnt(16)
	v_mov_b64_e32 v[102:103], v[156:157]
	global_load_dwordx2 v[156:157], v[170:171], off offset:32
	ds_read_b128 v[104:107], v172 offset:192
	v_lshlrev_b32_e32 v108, 16, v102
	s_waitcnt lgkmcnt(0)
	v_add_f32_e32 v98, v98, v104
	v_add_f32_e32 v99, v99, v105
	v_mul_f32_e32 v98, 0xbfb8aa3b, v98
	v_mul_f32_e32 v99, 0xbfb8aa3b, v99
	v_exp_f32_e32 v98, v98
	v_exp_f32_e32 v99, v99
	v_and_b32_e32 v102, 0xffff0000, v102
	v_lshlrev_b32_e32 v109, 16, v103
	v_add_f32_e32 v98, 1.0, v98
	v_add_f32_e32 v99, 1.0, v99
	v_rcp_f32_e32 v98, v98
	v_rcp_f32_e32 v99, v99
	v_and_b32_e32 v103, 0xffff0000, v103
	v_mul_f32_e32 v98, v98, v108
	v_mul_f32_e32 v99, v99, v102
	v_cvt_pk_bf16_f32 v250, v98, v99
	v_add_f32_e32 v99, v100, v106
	v_mul_f32_e32 v99, 0xbfb8aa3b, v99
	v_add_f32_e32 v100, v101, v107
	v_exp_f32_e32 v99, v99
	v_mul_f32_e32 v100, 0xbfb8aa3b, v100
	v_exp_f32_e32 v100, v100
	v_add_f32_e32 v99, 1.0, v99
	v_rcp_f32_e32 v99, v99
	v_add_f32_e32 v100, 1.0, v100
	v_rcp_f32_e32 v100, v100
	v_mul_f32_e32 v99, v99, v109
	v_mul_f32_e32 v100, v100, v103
	v_cvt_pk_bf16_f32 v251, v99, v100
	v_lshl_add_u64 v[252:253], v[110:111], 0, v[176:177]
	s_nop 1
	v_permlane16_swap_b32_e32 v248, v250
	v_permlane16_swap_b32_e32 v249, v251
	global_store_dwordx4 v[252:253], v[248:251], off offset:64
	v_lshl_add_u64 v[98:99], s[24:25], 0, v[200:201]
	v_lshl_add_u64 v[98:99], v[98:99], 0, v[0:1]
	s_waitcnt vmcnt(17)
	v_mov_b64_e32 v[104:105], v[158:159]
	global_load_dwordx2 v[158:159], v[170:171], off offset:64
	ds_read_b128 v[100:103], v172
	v_lshlrev_b32_e32 v106, 16, v104
	s_waitcnt lgkmcnt(0)
	v_add_f32_e32 v94, v94, v100
	v_add_f32_e32 v95, v95, v101
	v_mul_f32_e32 v94, 0xbfb8aa3b, v94
	v_mul_f32_e32 v95, 0xbfb8aa3b, v95
	v_exp_f32_e32 v94, v94
	v_exp_f32_e32 v95, v95
	v_and_b32_e32 v104, 0xffff0000, v104
	v_lshlrev_b32_e32 v107, 16, v105
	v_add_f32_e32 v94, 1.0, v94
	v_add_f32_e32 v95, 1.0, v95
	v_rcp_f32_e32 v94, v94
	v_rcp_f32_e32 v95, v95
	v_and_b32_e32 v105, 0xffff0000, v105
	v_mul_f32_e32 v94, v94, v106
	v_mul_f32_e32 v95, v95, v104
	v_cvt_pk_bf16_f32 v248, v94, v95
	v_add_f32_e32 v94, v96, v102
	v_add_f32_e32 v95, v97, v103
	v_mul_f32_e32 v94, 0xbfb8aa3b, v94
	v_mul_f32_e32 v95, 0xbfb8aa3b, v95
	v_exp_f32_e32 v94, v94
	v_exp_f32_e32 v95, v95
	v_add_f32_e32 v94, 1.0, v94
	v_add_f32_e32 v95, 1.0, v95
	v_rcp_f32_e32 v94, v94
	v_rcp_f32_e32 v95, v95
	v_mul_f32_e32 v94, v94, v107
	v_mul_f32_e32 v95, v95, v105
	v_cvt_pk_bf16_f32 v249, v94, v95
	v_lshl_add_u64 v[94:95], s[22:23], 0, v[200:201]
	v_lshl_add_u64 v[94:95], v[94:95], 0, v[0:1]
	s_waitcnt vmcnt(17)
	v_mov_b64_e32 v[96:97], v[160:161]
	global_load_dwordx2 v[160:161], v[170:171], off offset:96
	v_add_co_u32_e32 v170, vcc, 0x8000, v170
	s_nop 1
	v_addc_co_u32_e32 v171, vcc, 0, v171, vcc
	ds_read_b128 v[100:103], v172 offset:64
	v_lshlrev_b32_e32 v104, 16, v96
	s_waitcnt lgkmcnt(0)
	v_add_f32_e32 v90, v90, v100
	v_add_f32_e32 v91, v91, v101
	v_mul_f32_e32 v90, 0xbfb8aa3b, v90
	v_mul_f32_e32 v91, 0xbfb8aa3b, v91
	v_exp_f32_e32 v90, v90
	v_exp_f32_e32 v91, v91
	v_and_b32_e32 v96, 0xffff0000, v96
	v_lshlrev_b32_e32 v105, 16, v97
	v_add_f32_e32 v90, 1.0, v90
	v_add_f32_e32 v91, 1.0, v91
	v_rcp_f32_e32 v90, v90
	v_rcp_f32_e32 v91, v91
	v_and_b32_e32 v97, 0xffff0000, v97
	v_mul_f32_e32 v90, v90, v104
	v_mul_f32_e32 v91, v91, v96
	v_cvt_pk_bf16_f32 v250, v90, v91
	v_add_f32_e32 v91, v92, v102
	v_mul_f32_e32 v91, 0xbfb8aa3b, v91
	v_add_f32_e32 v92, v93, v103
	v_exp_f32_e32 v91, v91
	v_mul_f32_e32 v92, 0xbfb8aa3b, v92
	v_exp_f32_e32 v92, v92
	v_add_f32_e32 v91, 1.0, v91
	v_rcp_f32_e32 v91, v91
	v_add_f32_e32 v92, 1.0, v92
	v_rcp_f32_e32 v92, v92
	v_mul_f32_e32 v91, v91, v105
	v_mul_f32_e32 v92, v92, v97
	v_cvt_pk_bf16_f32 v251, v91, v92
	v_lshl_add_u64 v[252:253], v[94:95], 0, v[176:177]
	s_nop 1
	v_permlane16_swap_b32_e32 v248, v250
	v_permlane16_swap_b32_e32 v249, v251
	global_store_dwordx4 v[252:253], v[248:251], off
	s_waitcnt vmcnt(18)
	v_mov_b64_e32 v[96:97], v[162:163]
	global_load_dwordx2 v[162:163], v[170:171], off
	ds_read_b128 v[90:93], v172 offset:128
	v_lshlrev_b32_e32 v100, 16, v96
	s_waitcnt lgkmcnt(0)
	v_add_f32_e32 v86, v86, v90
	v_add_f32_e32 v87, v87, v91
	v_mul_f32_e32 v86, 0xbfb8aa3b, v86
	v_mul_f32_e32 v87, 0xbfb8aa3b, v87
	v_exp_f32_e32 v86, v86
	v_exp_f32_e32 v87, v87
	v_and_b32_e32 v96, 0xffff0000, v96
	v_lshlrev_b32_e32 v101, 16, v97
	v_add_f32_e32 v86, 1.0, v86
	v_add_f32_e32 v87, 1.0, v87
	v_rcp_f32_e32 v86, v86
	v_rcp_f32_e32 v87, v87
	v_and_b32_e32 v97, 0xffff0000, v97
	v_mul_f32_e32 v86, v86, v100
	v_mul_f32_e32 v87, v87, v96
	v_cvt_pk_bf16_f32 v248, v86, v87
	v_add_f32_e32 v87, v88, v92
	v_mul_f32_e32 v87, 0xbfb8aa3b, v87
	v_add_f32_e32 v88, v89, v93
	v_exp_f32_e32 v87, v87
	v_mul_f32_e32 v88, 0xbfb8aa3b, v88
	v_exp_f32_e32 v88, v88
	v_add_f32_e32 v87, 1.0, v87
	v_rcp_f32_e32 v87, v87
	v_add_f32_e32 v88, 1.0, v88
	v_rcp_f32_e32 v88, v88
	v_mul_f32_e32 v87, v87, v101
	v_mul_f32_e32 v88, v88, v97
	v_cvt_pk_bf16_f32 v249, v87, v88
	s_waitcnt vmcnt(18)
	v_mov_b64_e32 v[86:87], v[164:165]
	global_load_dwordx2 v[164:165], v[170:171], off offset:32
	ds_read_b128 v[88:91], v172 offset:192
	v_lshlrev_b32_e32 v92, 16, v86
	s_waitcnt lgkmcnt(0)
	v_add_f32_e32 v82, v82, v88
	v_add_f32_e32 v83, v83, v89
	v_mul_f32_e32 v82, 0xbfb8aa3b, v82
	v_mul_f32_e32 v83, 0xbfb8aa3b, v83
	v_exp_f32_e32 v82, v82
	v_exp_f32_e32 v83, v83
	v_and_b32_e32 v86, 0xffff0000, v86
	v_lshlrev_b32_e32 v93, 16, v87
	v_add_f32_e32 v82, 1.0, v82
	v_add_f32_e32 v83, 1.0, v83
	v_rcp_f32_e32 v82, v82
	v_rcp_f32_e32 v83, v83
	v_and_b32_e32 v87, 0xffff0000, v87
	v_mul_f32_e32 v82, v82, v92
	v_mul_f32_e32 v83, v83, v86
	v_cvt_pk_bf16_f32 v250, v82, v83
	v_add_f32_e32 v83, v84, v90
	v_mul_f32_e32 v83, 0xbfb8aa3b, v83
	v_add_f32_e32 v84, v85, v91
	v_exp_f32_e32 v83, v83
	v_mul_f32_e32 v84, 0xbfb8aa3b, v84
	v_exp_f32_e32 v84, v84
	v_add_f32_e32 v83, 1.0, v83
	v_rcp_f32_e32 v83, v83
	v_add_f32_e32 v84, 1.0, v84
	v_rcp_f32_e32 v84, v84
	v_mul_f32_e32 v83, v83, v93
	v_mul_f32_e32 v84, v84, v87
	v_cvt_pk_bf16_f32 v251, v83, v84
	v_lshl_add_u64 v[252:253], v[94:95], 0, v[176:177]
	s_nop 1
	v_permlane16_swap_b32_e32 v248, v250
	v_permlane16_swap_b32_e32 v249, v251
	global_store_dwordx4 v[252:253], v[248:251], off offset:64
	v_lshl_add_u64 v[82:83], s[24:25], 0, v[202:203]
	v_lshl_add_u64 v[82:83], v[82:83], 0, v[0:1]
	s_waitcnt vmcnt(19)
	v_mov_b64_e32 v[88:89], v[166:167]
	global_load_dwordx2 v[166:167], v[170:171], off offset:64
	ds_read_b128 v[84:87], v172
	v_lshlrev_b32_e32 v90, 16, v88
	s_waitcnt lgkmcnt(0)
	v_add_f32_e32 v78, v78, v84
	v_add_f32_e32 v79, v79, v85
	v_mul_f32_e32 v78, 0xbfb8aa3b, v78
	v_mul_f32_e32 v79, 0xbfb8aa3b, v79
	v_exp_f32_e32 v78, v78
	v_exp_f32_e32 v79, v79
	v_and_b32_e32 v88, 0xffff0000, v88
	v_lshlrev_b32_e32 v91, 16, v89
	v_add_f32_e32 v78, 1.0, v78
	v_add_f32_e32 v79, 1.0, v79
	v_rcp_f32_e32 v78, v78
	v_rcp_f32_e32 v79, v79
	v_and_b32_e32 v89, 0xffff0000, v89
	v_mul_f32_e32 v78, v78, v90
	v_mul_f32_e32 v79, v79, v88
	v_cvt_pk_bf16_f32 v248, v78, v79
	v_add_f32_e32 v78, v80, v86
	v_add_f32_e32 v79, v81, v87
	v_mul_f32_e32 v78, 0xbfb8aa3b, v78
	v_mul_f32_e32 v79, 0xbfb8aa3b, v79
	v_exp_f32_e32 v78, v78
	v_exp_f32_e32 v79, v79
	v_add_f32_e32 v78, 1.0, v78
	v_add_f32_e32 v79, 1.0, v79
	v_rcp_f32_e32 v78, v78
	v_rcp_f32_e32 v79, v79
	v_mul_f32_e32 v78, v78, v91
	v_mul_f32_e32 v79, v79, v89
	v_cvt_pk_bf16_f32 v249, v78, v79
	v_lshl_add_u64 v[78:79], s[22:23], 0, v[202:203]
	v_lshl_add_u64 v[78:79], v[78:79], 0, v[0:1]
	s_waitcnt vmcnt(19)
	v_mov_b64_e32 v[80:81], v[168:169]
	global_load_dwordx2 v[168:169], v[170:171], off offset:96
	v_add_co_u32_e32 v170, vcc, 0x8000, v170
	s_nop 1
	v_addc_co_u32_e32 v171, vcc, 0, v171, vcc
	ds_read_b128 v[84:87], v172 offset:64
	v_lshlrev_b32_e32 v88, 16, v80
	s_waitcnt lgkmcnt(0)
	v_add_f32_e32 v74, v74, v84
	v_add_f32_e32 v75, v75, v85
	v_mul_f32_e32 v74, 0xbfb8aa3b, v74
	v_mul_f32_e32 v75, 0xbfb8aa3b, v75
	v_exp_f32_e32 v74, v74
	v_exp_f32_e32 v75, v75
	v_and_b32_e32 v80, 0xffff0000, v80
	v_lshlrev_b32_e32 v89, 16, v81
	v_add_f32_e32 v74, 1.0, v74
	v_add_f32_e32 v75, 1.0, v75
	v_rcp_f32_e32 v74, v74
	v_rcp_f32_e32 v75, v75
	v_and_b32_e32 v81, 0xffff0000, v81
	v_mul_f32_e32 v74, v74, v88
	v_mul_f32_e32 v75, v75, v80
	v_cvt_pk_bf16_f32 v250, v74, v75
	v_add_f32_e32 v75, v76, v86
	v_mul_f32_e32 v75, 0xbfb8aa3b, v75
	v_add_f32_e32 v76, v77, v87
	v_exp_f32_e32 v75, v75
	v_mul_f32_e32 v76, 0xbfb8aa3b, v76
	v_exp_f32_e32 v76, v76
	v_add_f32_e32 v75, 1.0, v75
	v_rcp_f32_e32 v75, v75
	v_add_f32_e32 v76, 1.0, v76
	v_rcp_f32_e32 v76, v76
	v_mul_f32_e32 v75, v75, v89
	v_mul_f32_e32 v76, v76, v81
	v_cvt_pk_bf16_f32 v251, v75, v76
	v_lshl_add_u64 v[252:253], v[78:79], 0, v[176:177]
	s_nop 1
	v_permlane16_swap_b32_e32 v248, v250
	v_permlane16_swap_b32_e32 v249, v251
	global_store_dwordx4 v[252:253], v[248:251], off
	s_waitcnt vmcnt(20)
	v_mov_b64_e32 v[80:81], v[142:143]
	global_load_dwordx2 v[142:143], v[170:171], off
	ds_read_b128 v[74:77], v172 offset:128
	v_lshlrev_b32_e32 v84, 16, v80
	s_waitcnt lgkmcnt(0)
	v_add_f32_e32 v70, v70, v74
	v_add_f32_e32 v71, v71, v75
	v_mul_f32_e32 v70, 0xbfb8aa3b, v70
	v_mul_f32_e32 v71, 0xbfb8aa3b, v71
	v_exp_f32_e32 v70, v70
	v_exp_f32_e32 v71, v71
	v_and_b32_e32 v80, 0xffff0000, v80
	v_lshlrev_b32_e32 v85, 16, v81
	v_add_f32_e32 v70, 1.0, v70
	v_add_f32_e32 v71, 1.0, v71
	v_rcp_f32_e32 v70, v70
	v_rcp_f32_e32 v71, v71
	v_and_b32_e32 v81, 0xffff0000, v81
	v_mul_f32_e32 v70, v70, v84
	v_mul_f32_e32 v71, v71, v80
	v_cvt_pk_bf16_f32 v248, v70, v71
	v_add_f32_e32 v71, v72, v76
	v_mul_f32_e32 v71, 0xbfb8aa3b, v71
	v_add_f32_e32 v72, v73, v77
	v_exp_f32_e32 v71, v71
	v_mul_f32_e32 v72, 0xbfb8aa3b, v72
	v_exp_f32_e32 v72, v72
	v_add_f32_e32 v71, 1.0, v71
	v_rcp_f32_e32 v71, v71
	v_add_f32_e32 v72, 1.0, v72
	v_rcp_f32_e32 v72, v72
	v_mul_f32_e32 v71, v71, v85
	v_mul_f32_e32 v72, v72, v81
	v_cvt_pk_bf16_f32 v249, v71, v72
	s_waitcnt vmcnt(20)
	v_mov_b64_e32 v[70:71], v[144:145]
	global_load_dwordx2 v[144:145], v[170:171], off offset:32
	ds_read_b128 v[72:75], v172 offset:192
	v_lshlrev_b32_e32 v76, 16, v70
	s_waitcnt lgkmcnt(0)
	v_add_f32_e32 v66, v66, v72
	v_add_f32_e32 v67, v67, v73
	v_mul_f32_e32 v66, 0xbfb8aa3b, v66
	v_mul_f32_e32 v67, 0xbfb8aa3b, v67
	v_exp_f32_e32 v66, v66
	v_exp_f32_e32 v67, v67
	v_and_b32_e32 v70, 0xffff0000, v70
	v_lshlrev_b32_e32 v77, 16, v71
	v_add_f32_e32 v66, 1.0, v66
	v_add_f32_e32 v67, 1.0, v67
	v_rcp_f32_e32 v66, v66
	v_rcp_f32_e32 v67, v67
	v_and_b32_e32 v71, 0xffff0000, v71
	v_mul_f32_e32 v66, v66, v76
	v_mul_f32_e32 v67, v67, v70
	v_cvt_pk_bf16_f32 v250, v66, v67
	v_add_f32_e32 v67, v68, v74
	v_mul_f32_e32 v67, 0xbfb8aa3b, v67
	v_add_f32_e32 v68, v69, v75
	v_exp_f32_e32 v67, v67
	v_mul_f32_e32 v68, 0xbfb8aa3b, v68
	v_exp_f32_e32 v68, v68
	v_add_f32_e32 v67, 1.0, v67
	v_rcp_f32_e32 v67, v67
	v_add_f32_e32 v68, 1.0, v68
	v_rcp_f32_e32 v68, v68
	v_mul_f32_e32 v67, v67, v77
	v_mul_f32_e32 v68, v68, v71
	v_cvt_pk_bf16_f32 v251, v67, v68
	v_lshl_add_u64 v[252:253], v[78:79], 0, v[176:177]
	s_nop 1
	v_permlane16_swap_b32_e32 v248, v250
	v_permlane16_swap_b32_e32 v249, v251
	global_store_dwordx4 v[252:253], v[248:251], off offset:64
	v_lshl_add_u64 v[66:67], s[24:25], 0, v[204:205]
	v_lshl_add_u64 v[66:67], v[66:67], 0, v[0:1]
	s_waitcnt vmcnt(20)
	v_mov_b64_e32 v[72:73], v[146:147]
	global_load_dwordx2 v[146:147], v[170:171], off offset:64
	ds_read_b128 v[68:71], v172
	v_lshlrev_b32_e32 v74, 16, v72
	s_waitcnt lgkmcnt(0)
	v_add_f32_e32 v62, v62, v68
	v_add_f32_e32 v63, v63, v69
	v_mul_f32_e32 v62, 0xbfb8aa3b, v62
	v_mul_f32_e32 v63, 0xbfb8aa3b, v63
	v_exp_f32_e32 v62, v62
	v_exp_f32_e32 v63, v63
	v_and_b32_e32 v72, 0xffff0000, v72
	v_lshlrev_b32_e32 v75, 16, v73
	v_add_f32_e32 v62, 1.0, v62
	v_add_f32_e32 v63, 1.0, v63
	v_rcp_f32_e32 v62, v62
	v_rcp_f32_e32 v63, v63
	v_and_b32_e32 v73, 0xffff0000, v73
	v_mul_f32_e32 v62, v62, v74
	v_mul_f32_e32 v63, v63, v72
	v_cvt_pk_bf16_f32 v248, v62, v63
	v_add_f32_e32 v62, v64, v70
	v_add_f32_e32 v63, v65, v71
	v_mul_f32_e32 v62, 0xbfb8aa3b, v62
	v_mul_f32_e32 v63, 0xbfb8aa3b, v63
	v_exp_f32_e32 v62, v62
	v_exp_f32_e32 v63, v63
	v_add_f32_e32 v62, 1.0, v62
	v_add_f32_e32 v63, 1.0, v63
	v_rcp_f32_e32 v62, v62
	v_rcp_f32_e32 v63, v63
	v_mul_f32_e32 v62, v62, v75
	v_mul_f32_e32 v63, v63, v73
	v_cvt_pk_bf16_f32 v249, v62, v63
	v_lshl_add_u64 v[62:63], s[22:23], 0, v[204:205]
	v_lshl_add_u64 v[62:63], v[62:63], 0, v[0:1]
	s_waitcnt vmcnt(20)
	v_mov_b64_e32 v[64:65], v[148:149]
	global_load_dwordx2 v[148:149], v[170:171], off offset:96
	ds_read_b128 v[68:71], v172 offset:64
	v_lshlrev_b32_e32 v72, 16, v64
	s_waitcnt lgkmcnt(0)
	v_add_f32_e32 v58, v58, v68
	v_add_f32_e32 v59, v59, v69
	v_mul_f32_e32 v58, 0xbfb8aa3b, v58
	v_mul_f32_e32 v59, 0xbfb8aa3b, v59
	v_exp_f32_e32 v58, v58
	v_exp_f32_e32 v59, v59
	v_and_b32_e32 v64, 0xffff0000, v64
	v_lshlrev_b32_e32 v73, 16, v65
	v_add_f32_e32 v58, 1.0, v58
	v_add_f32_e32 v59, 1.0, v59
	v_rcp_f32_e32 v58, v58
	v_rcp_f32_e32 v59, v59
	v_and_b32_e32 v65, 0xffff0000, v65
	v_mul_f32_e32 v58, v58, v72
	v_mul_f32_e32 v59, v59, v64
	v_cvt_pk_bf16_f32 v250, v58, v59
	v_add_f32_e32 v59, v60, v70
	v_mul_f32_e32 v59, 0xbfb8aa3b, v59
	v_add_f32_e32 v60, v61, v71
	v_exp_f32_e32 v59, v59
	v_mul_f32_e32 v60, 0xbfb8aa3b, v60
	v_exp_f32_e32 v60, v60
	v_add_f32_e32 v59, 1.0, v59
	v_rcp_f32_e32 v59, v59
	v_add_f32_e32 v60, 1.0, v60
	v_rcp_f32_e32 v60, v60
	v_mul_f32_e32 v59, v59, v73
	v_mul_f32_e32 v60, v60, v65
	v_cvt_pk_bf16_f32 v251, v59, v60
	v_lshl_add_u64 v[252:253], v[62:63], 0, v[176:177]
	s_nop 1
	v_permlane16_swap_b32_e32 v248, v250
	v_permlane16_swap_b32_e32 v249, v251
	global_store_dwordx4 v[252:253], v[248:251], off
	s_waitcnt vmcnt(20)
	v_mov_b64_e32 v[64:65], v[150:151]
	ds_read_b128 v[58:61], v172 offset:128
	v_lshlrev_b32_e32 v68, 16, v64
	s_waitcnt lgkmcnt(0)
	v_add_f32_e32 v54, v54, v58
	v_add_f32_e32 v55, v55, v59
	v_mul_f32_e32 v54, 0xbfb8aa3b, v54
	v_mul_f32_e32 v55, 0xbfb8aa3b, v55
	v_exp_f32_e32 v54, v54
	v_exp_f32_e32 v55, v55
	v_and_b32_e32 v64, 0xffff0000, v64
	v_lshlrev_b32_e32 v69, 16, v65
	v_add_f32_e32 v54, 1.0, v54
	v_add_f32_e32 v55, 1.0, v55
	v_rcp_f32_e32 v54, v54
	v_rcp_f32_e32 v55, v55
	v_and_b32_e32 v65, 0xffff0000, v65
	v_mul_f32_e32 v54, v54, v68
	v_mul_f32_e32 v55, v55, v64
	v_cvt_pk_bf16_f32 v248, v54, v55
	v_add_f32_e32 v55, v56, v60
	v_mul_f32_e32 v55, 0xbfb8aa3b, v55
	v_add_f32_e32 v56, v57, v61
	v_exp_f32_e32 v55, v55
	v_mul_f32_e32 v56, 0xbfb8aa3b, v56
	v_exp_f32_e32 v56, v56
	v_add_f32_e32 v55, 1.0, v55
	v_rcp_f32_e32 v55, v55
	v_add_f32_e32 v56, 1.0, v56
	v_rcp_f32_e32 v56, v56
	v_mul_f32_e32 v55, v55, v69
	v_mul_f32_e32 v56, v56, v65
	v_cvt_pk_bf16_f32 v249, v55, v56
	s_waitcnt vmcnt(19)
	v_mov_b64_e32 v[54:55], v[152:153]
	ds_read_b128 v[56:59], v172 offset:192
	v_lshlrev_b32_e32 v60, 16, v54
	s_waitcnt lgkmcnt(0)
	v_add_f32_e32 v50, v50, v56
	v_add_f32_e32 v51, v51, v57
	v_mul_f32_e32 v50, 0xbfb8aa3b, v50
	v_mul_f32_e32 v51, 0xbfb8aa3b, v51
	v_exp_f32_e32 v50, v50
	v_exp_f32_e32 v51, v51
	v_and_b32_e32 v54, 0xffff0000, v54
	v_lshlrev_b32_e32 v61, 16, v55
	v_add_f32_e32 v50, 1.0, v50
	v_add_f32_e32 v51, 1.0, v51
	v_rcp_f32_e32 v50, v50
	v_rcp_f32_e32 v51, v51
	v_and_b32_e32 v55, 0xffff0000, v55
	v_mul_f32_e32 v50, v50, v60
	v_mul_f32_e32 v51, v51, v54
	v_cvt_pk_bf16_f32 v250, v50, v51
	v_add_f32_e32 v51, v52, v58
	v_mul_f32_e32 v51, 0xbfb8aa3b, v51
	v_add_f32_e32 v52, v53, v59
	v_exp_f32_e32 v51, v51
	v_mul_f32_e32 v52, 0xbfb8aa3b, v52
	v_exp_f32_e32 v52, v52
	v_add_f32_e32 v51, 1.0, v51
	v_rcp_f32_e32 v51, v51
	v_add_f32_e32 v52, 1.0, v52
	v_rcp_f32_e32 v52, v52
	v_mul_f32_e32 v51, v51, v61
	v_mul_f32_e32 v52, v52, v55
	v_cvt_pk_bf16_f32 v251, v51, v52
	v_lshl_add_u64 v[252:253], v[62:63], 0, v[176:177]
	s_nop 1
	v_permlane16_swap_b32_e32 v248, v250
	v_permlane16_swap_b32_e32 v249, v251
	global_store_dwordx4 v[252:253], v[248:251], off offset:64
	v_lshl_add_u64 v[50:51], s[24:25], 0, v[206:207]
	v_lshl_add_u64 v[50:51], v[50:51], 0, v[0:1]
	s_waitcnt vmcnt(18)
	v_mov_b64_e32 v[56:57], v[154:155]
	ds_read_b128 v[52:55], v172
	v_lshlrev_b32_e32 v58, 16, v56
	s_waitcnt lgkmcnt(0)
	v_add_f32_e32 v46, v46, v52
	v_add_f32_e32 v47, v47, v53
	v_mul_f32_e32 v46, 0xbfb8aa3b, v46
	v_mul_f32_e32 v47, 0xbfb8aa3b, v47
	v_exp_f32_e32 v46, v46
	v_exp_f32_e32 v47, v47
	v_and_b32_e32 v56, 0xffff0000, v56
	v_lshlrev_b32_e32 v59, 16, v57
	v_add_f32_e32 v46, 1.0, v46
	v_add_f32_e32 v47, 1.0, v47
	v_rcp_f32_e32 v46, v46
	v_rcp_f32_e32 v47, v47
	v_and_b32_e32 v57, 0xffff0000, v57
	v_mul_f32_e32 v46, v46, v58
	v_mul_f32_e32 v47, v47, v56
	v_cvt_pk_bf16_f32 v248, v46, v47
	v_add_f32_e32 v46, v48, v54
	v_add_f32_e32 v47, v49, v55
	v_mul_f32_e32 v46, 0xbfb8aa3b, v46
	v_mul_f32_e32 v47, 0xbfb8aa3b, v47
	v_exp_f32_e32 v46, v46
	v_exp_f32_e32 v47, v47
	v_add_f32_e32 v46, 1.0, v46
	v_add_f32_e32 v47, 1.0, v47
	v_rcp_f32_e32 v46, v46
	v_rcp_f32_e32 v47, v47
	v_mul_f32_e32 v46, v46, v59
	v_mul_f32_e32 v47, v47, v57
	v_cvt_pk_bf16_f32 v249, v46, v47
	v_lshl_add_u64 v[46:47], s[22:23], 0, v[206:207]
	v_lshl_add_u64 v[46:47], v[46:47], 0, v[0:1]
	s_waitcnt vmcnt(17)
	v_mov_b64_e32 v[48:49], v[156:157]
	ds_read_b128 v[52:55], v172 offset:64
	v_lshlrev_b32_e32 v56, 16, v48
	s_waitcnt lgkmcnt(0)
	v_add_f32_e32 v42, v42, v52
	v_add_f32_e32 v43, v43, v53
	v_mul_f32_e32 v42, 0xbfb8aa3b, v42
	v_mul_f32_e32 v43, 0xbfb8aa3b, v43
	v_exp_f32_e32 v42, v42
	v_exp_f32_e32 v43, v43
	v_and_b32_e32 v48, 0xffff0000, v48
	v_lshlrev_b32_e32 v57, 16, v49
	v_add_f32_e32 v42, 1.0, v42
	v_add_f32_e32 v43, 1.0, v43
	v_rcp_f32_e32 v42, v42
	v_rcp_f32_e32 v43, v43
	v_and_b32_e32 v49, 0xffff0000, v49
	v_mul_f32_e32 v42, v42, v56
	v_mul_f32_e32 v43, v43, v48
	v_cvt_pk_bf16_f32 v250, v42, v43
	v_add_f32_e32 v43, v44, v54
	v_mul_f32_e32 v43, 0xbfb8aa3b, v43
	v_add_f32_e32 v44, v45, v55
	v_exp_f32_e32 v43, v43
	v_mul_f32_e32 v44, 0xbfb8aa3b, v44
	v_exp_f32_e32 v44, v44
	v_add_f32_e32 v43, 1.0, v43
	v_rcp_f32_e32 v43, v43
	v_add_f32_e32 v44, 1.0, v44
	v_rcp_f32_e32 v44, v44
	v_mul_f32_e32 v43, v43, v57
	v_mul_f32_e32 v44, v44, v49
	v_cvt_pk_bf16_f32 v251, v43, v44
	v_lshl_add_u64 v[252:253], v[46:47], 0, v[176:177]
	s_nop 1
	v_permlane16_swap_b32_e32 v248, v250
	v_permlane16_swap_b32_e32 v249, v251
	global_store_dwordx4 v[252:253], v[248:251], off
	s_waitcnt vmcnt(16)
	v_mov_b64_e32 v[48:49], v[158:159]
	ds_read_b128 v[42:45], v172 offset:128
	v_lshlrev_b32_e32 v52, 16, v48
	s_waitcnt lgkmcnt(0)
	v_add_f32_e32 v38, v38, v42
	v_add_f32_e32 v39, v39, v43
	v_mul_f32_e32 v38, 0xbfb8aa3b, v38
	v_mul_f32_e32 v39, 0xbfb8aa3b, v39
	v_exp_f32_e32 v38, v38
	v_exp_f32_e32 v39, v39
	v_and_b32_e32 v48, 0xffff0000, v48
	v_lshlrev_b32_e32 v53, 16, v49
	v_add_f32_e32 v38, 1.0, v38
	v_add_f32_e32 v39, 1.0, v39
	v_rcp_f32_e32 v38, v38
	v_rcp_f32_e32 v39, v39
	v_and_b32_e32 v49, 0xffff0000, v49
	v_mul_f32_e32 v38, v38, v52
	v_mul_f32_e32 v39, v39, v48
	v_cvt_pk_bf16_f32 v248, v38, v39
	v_add_f32_e32 v39, v40, v44
	v_mul_f32_e32 v39, 0xbfb8aa3b, v39
	v_add_f32_e32 v40, v41, v45
	v_exp_f32_e32 v39, v39
	v_mul_f32_e32 v40, 0xbfb8aa3b, v40
	v_exp_f32_e32 v40, v40
	v_add_f32_e32 v39, 1.0, v39
	v_rcp_f32_e32 v39, v39
	v_add_f32_e32 v40, 1.0, v40
	v_rcp_f32_e32 v40, v40
	v_mul_f32_e32 v39, v39, v53
	v_mul_f32_e32 v40, v40, v49
	v_cvt_pk_bf16_f32 v249, v39, v40
	s_waitcnt vmcnt(15)
	v_mov_b64_e32 v[38:39], v[160:161]
	ds_read_b128 v[40:43], v172 offset:192
	v_lshlrev_b32_e32 v44, 16, v38
	s_waitcnt lgkmcnt(0)
	v_add_f32_e32 v34, v34, v40
	v_add_f32_e32 v35, v35, v41
	v_mul_f32_e32 v34, 0xbfb8aa3b, v34
	v_mul_f32_e32 v35, 0xbfb8aa3b, v35
	v_exp_f32_e32 v34, v34
	v_exp_f32_e32 v35, v35
	v_and_b32_e32 v38, 0xffff0000, v38
	v_lshlrev_b32_e32 v45, 16, v39
	v_add_f32_e32 v34, 1.0, v34
	v_add_f32_e32 v35, 1.0, v35
	v_rcp_f32_e32 v34, v34
	v_rcp_f32_e32 v35, v35
	v_and_b32_e32 v39, 0xffff0000, v39
	v_mul_f32_e32 v34, v34, v44
	v_mul_f32_e32 v35, v35, v38
	v_cvt_pk_bf16_f32 v250, v34, v35
	v_add_f32_e32 v35, v36, v42
	v_mul_f32_e32 v35, 0xbfb8aa3b, v35
	v_add_f32_e32 v36, v37, v43
	v_exp_f32_e32 v35, v35
	v_mul_f32_e32 v36, 0xbfb8aa3b, v36
	v_exp_f32_e32 v36, v36
	v_add_f32_e32 v35, 1.0, v35
	v_rcp_f32_e32 v35, v35
	v_add_f32_e32 v36, 1.0, v36
	v_rcp_f32_e32 v36, v36
	v_mul_f32_e32 v35, v35, v45
	v_mul_f32_e32 v36, v36, v39
	v_cvt_pk_bf16_f32 v251, v35, v36
	v_lshl_add_u64 v[252:253], v[46:47], 0, v[176:177]
	s_nop 1
	v_permlane16_swap_b32_e32 v248, v250
	v_permlane16_swap_b32_e32 v249, v251
	global_store_dwordx4 v[252:253], v[248:251], off offset:64
	v_lshl_add_u64 v[34:35], s[24:25], 0, v[208:209]
	v_lshl_add_u64 v[34:35], v[34:35], 0, v[0:1]
	s_waitcnt vmcnt(14)
	v_mov_b64_e32 v[40:41], v[162:163]
	ds_read_b128 v[36:39], v172
	v_lshlrev_b32_e32 v42, 16, v40
	s_waitcnt lgkmcnt(0)
	v_add_f32_e32 v30, v30, v36
	v_add_f32_e32 v31, v31, v37
	v_mul_f32_e32 v30, 0xbfb8aa3b, v30
	v_mul_f32_e32 v31, 0xbfb8aa3b, v31
	v_exp_f32_e32 v30, v30
	v_exp_f32_e32 v31, v31
	v_and_b32_e32 v40, 0xffff0000, v40
	v_lshlrev_b32_e32 v43, 16, v41
	v_add_f32_e32 v30, 1.0, v30
	v_add_f32_e32 v31, 1.0, v31
	v_rcp_f32_e32 v30, v30
	v_rcp_f32_e32 v31, v31
	v_and_b32_e32 v41, 0xffff0000, v41
	v_mul_f32_e32 v30, v30, v42
	v_mul_f32_e32 v31, v31, v40
	v_cvt_pk_bf16_f32 v248, v30, v31
	v_add_f32_e32 v30, v32, v38
	v_add_f32_e32 v31, v33, v39
	v_mul_f32_e32 v30, 0xbfb8aa3b, v30
	v_mul_f32_e32 v31, 0xbfb8aa3b, v31
	v_exp_f32_e32 v30, v30
	v_exp_f32_e32 v31, v31
	v_add_f32_e32 v30, 1.0, v30
	v_add_f32_e32 v31, 1.0, v31
	v_rcp_f32_e32 v30, v30
	v_rcp_f32_e32 v31, v31
	v_mul_f32_e32 v30, v30, v43
	v_mul_f32_e32 v31, v31, v41
	v_cvt_pk_bf16_f32 v249, v30, v31
	v_lshl_add_u64 v[30:31], s[22:23], 0, v[208:209]
	v_lshl_add_u64 v[30:31], v[30:31], 0, v[0:1]
	s_waitcnt vmcnt(13)
	v_mov_b64_e32 v[32:33], v[164:165]
	ds_read_b128 v[36:39], v172 offset:64
	v_lshlrev_b32_e32 v40, 16, v32
	s_waitcnt lgkmcnt(0)
	v_add_f32_e32 v26, v26, v36
	v_add_f32_e32 v27, v27, v37
	v_mul_f32_e32 v26, 0xbfb8aa3b, v26
	v_mul_f32_e32 v27, 0xbfb8aa3b, v27
	v_exp_f32_e32 v26, v26
	v_exp_f32_e32 v27, v27
	v_and_b32_e32 v32, 0xffff0000, v32
	v_lshlrev_b32_e32 v41, 16, v33
	v_add_f32_e32 v26, 1.0, v26
	v_add_f32_e32 v27, 1.0, v27
	v_rcp_f32_e32 v26, v26
	v_rcp_f32_e32 v27, v27
	v_and_b32_e32 v33, 0xffff0000, v33
	v_mul_f32_e32 v26, v26, v40
	v_mul_f32_e32 v27, v27, v32
	v_cvt_pk_bf16_f32 v250, v26, v27
	v_add_f32_e32 v27, v28, v38
	v_mul_f32_e32 v27, 0xbfb8aa3b, v27
	v_add_f32_e32 v28, v29, v39
	v_exp_f32_e32 v27, v27
	v_mul_f32_e32 v28, 0xbfb8aa3b, v28
	v_exp_f32_e32 v28, v28
	v_add_f32_e32 v27, 1.0, v27
	v_rcp_f32_e32 v27, v27
	v_add_f32_e32 v28, 1.0, v28
	v_rcp_f32_e32 v28, v28
	v_mul_f32_e32 v27, v27, v41
	v_mul_f32_e32 v28, v28, v33
	v_cvt_pk_bf16_f32 v251, v27, v28
	v_lshl_add_u64 v[252:253], v[30:31], 0, v[176:177]
	s_nop 1
	v_permlane16_swap_b32_e32 v248, v250
	v_permlane16_swap_b32_e32 v249, v251
	global_store_dwordx4 v[252:253], v[248:251], off
	s_waitcnt vmcnt(12)
	v_mov_b64_e32 v[32:33], v[166:167]
	ds_read_b128 v[26:29], v172 offset:128
	v_lshlrev_b32_e32 v36, 16, v32
	s_waitcnt lgkmcnt(0)
	v_add_f32_e32 v22, v22, v26
	v_add_f32_e32 v23, v23, v27
	v_mul_f32_e32 v22, 0xbfb8aa3b, v22
	v_mul_f32_e32 v23, 0xbfb8aa3b, v23
	v_exp_f32_e32 v22, v22
	v_exp_f32_e32 v23, v23
	v_and_b32_e32 v32, 0xffff0000, v32
	v_lshlrev_b32_e32 v37, 16, v33
	v_add_f32_e32 v22, 1.0, v22
	v_add_f32_e32 v23, 1.0, v23
	v_rcp_f32_e32 v22, v22
	v_rcp_f32_e32 v23, v23
	v_and_b32_e32 v33, 0xffff0000, v33
	v_mul_f32_e32 v22, v22, v36
	v_mul_f32_e32 v23, v23, v32
	v_cvt_pk_bf16_f32 v248, v22, v23
	v_add_f32_e32 v23, v24, v28
	v_mul_f32_e32 v23, 0xbfb8aa3b, v23
	v_add_f32_e32 v24, v25, v29
	v_exp_f32_e32 v23, v23
	v_mul_f32_e32 v24, 0xbfb8aa3b, v24
	v_exp_f32_e32 v24, v24
	v_add_f32_e32 v23, 1.0, v23
	v_rcp_f32_e32 v23, v23
	v_add_f32_e32 v24, 1.0, v24
	v_rcp_f32_e32 v24, v24
	v_mul_f32_e32 v23, v23, v37
	v_mul_f32_e32 v24, v24, v33
	v_cvt_pk_bf16_f32 v249, v23, v24
	s_waitcnt vmcnt(11)
	v_mov_b64_e32 v[22:23], v[168:169]
	ds_read_b128 v[24:27], v172 offset:192
	v_lshlrev_b32_e32 v28, 16, v22
	s_waitcnt lgkmcnt(0)
	v_add_f32_e32 v18, v18, v24
	v_add_f32_e32 v19, v19, v25
	v_mul_f32_e32 v18, 0xbfb8aa3b, v18
	v_mul_f32_e32 v19, 0xbfb8aa3b, v19
	v_exp_f32_e32 v18, v18
	v_exp_f32_e32 v19, v19
	v_and_b32_e32 v22, 0xffff0000, v22
	v_lshlrev_b32_e32 v29, 16, v23
	v_add_f32_e32 v18, 1.0, v18
	v_add_f32_e32 v19, 1.0, v19
	v_rcp_f32_e32 v18, v18
	v_rcp_f32_e32 v19, v19
	v_and_b32_e32 v23, 0xffff0000, v23
	v_mul_f32_e32 v18, v18, v28
	v_mul_f32_e32 v19, v19, v22
	v_cvt_pk_bf16_f32 v250, v18, v19
	v_add_f32_e32 v19, v20, v26
	v_mul_f32_e32 v19, 0xbfb8aa3b, v19
	v_add_f32_e32 v20, v21, v27
	v_exp_f32_e32 v19, v19
	v_mul_f32_e32 v20, 0xbfb8aa3b, v20
	v_exp_f32_e32 v20, v20
	v_add_f32_e32 v19, 1.0, v19
	v_rcp_f32_e32 v19, v19
	v_add_f32_e32 v20, 1.0, v20
	v_rcp_f32_e32 v20, v20
	v_mul_f32_e32 v19, v19, v29
	v_mul_f32_e32 v20, v20, v23
	v_cvt_pk_bf16_f32 v251, v19, v20
	v_lshl_add_u64 v[252:253], v[30:31], 0, v[176:177]
	s_nop 1
	v_permlane16_swap_b32_e32 v248, v250
	v_permlane16_swap_b32_e32 v249, v251
	global_store_dwordx4 v[252:253], v[248:251], off offset:64
	v_lshl_add_u64 v[18:19], s[24:25], 0, v[210:211]
	v_lshl_add_u64 v[18:19], v[18:19], 0, v[0:1]
	s_waitcnt vmcnt(10)
	v_mov_b64_e32 v[24:25], v[142:143]
	ds_read_b128 v[20:23], v172
	v_lshlrev_b32_e32 v26, 16, v24
	s_waitcnt lgkmcnt(0)
	v_add_f32_e32 v14, v14, v20
	v_add_f32_e32 v15, v15, v21
	v_mul_f32_e32 v14, 0xbfb8aa3b, v14
	v_mul_f32_e32 v15, 0xbfb8aa3b, v15
	v_exp_f32_e32 v14, v14
	v_exp_f32_e32 v15, v15
	v_and_b32_e32 v24, 0xffff0000, v24
	v_lshlrev_b32_e32 v27, 16, v25
	v_add_f32_e32 v14, 1.0, v14
	v_add_f32_e32 v15, 1.0, v15
	v_rcp_f32_e32 v14, v14
	v_rcp_f32_e32 v15, v15
	v_and_b32_e32 v25, 0xffff0000, v25
	v_mul_f32_e32 v14, v14, v26
	v_mul_f32_e32 v15, v15, v24
	v_cvt_pk_bf16_f32 v248, v14, v15
	v_add_f32_e32 v14, v16, v22
	v_add_f32_e32 v15, v17, v23
	v_mul_f32_e32 v14, 0xbfb8aa3b, v14
	v_mul_f32_e32 v15, 0xbfb8aa3b, v15
	v_exp_f32_e32 v14, v14
	v_exp_f32_e32 v15, v15
	v_add_f32_e32 v14, 1.0, v14
	v_add_f32_e32 v15, 1.0, v15
	v_rcp_f32_e32 v14, v14
	v_rcp_f32_e32 v15, v15
	v_mul_f32_e32 v14, v14, v27
	v_mul_f32_e32 v15, v15, v25
	v_cvt_pk_bf16_f32 v249, v14, v15
	v_lshl_add_u64 v[14:15], s[22:23], 0, v[210:211]
	v_lshl_add_u64 v[14:15], v[14:15], 0, v[0:1]
	s_waitcnt vmcnt(9)
	v_mov_b64_e32 v[16:17], v[144:145]
	ds_read_b128 v[20:23], v172 offset:64
	v_lshlrev_b32_e32 v0, 16, v16
	s_waitcnt lgkmcnt(0)
	v_add_f32_e32 v10, v10, v20
	v_mul_f32_e32 v10, 0xbfb8aa3b, v10
	v_exp_f32_e32 v10, v10
	v_and_b32_e32 v16, 0xffff0000, v16
	v_lshlrev_b32_e32 v24, 16, v17
	v_and_b32_e32 v17, 0xffff0000, v17
	v_add_f32_e32 v10, 1.0, v10
	v_rcp_f32_e32 v10, v10
	s_nop 0
	v_mul_f32_e32 v0, v10, v0
	v_add_f32_e32 v10, v11, v21
	v_mul_f32_e32 v10, 0xbfb8aa3b, v10
	v_exp_f32_e32 v10, v10
	v_add_f32_e32 v11, v13, v23
	v_mul_f32_e32 v11, 0xbfb8aa3b, v11
	v_exp_f32_e32 v11, v11
	v_add_f32_e32 v10, 1.0, v10
	v_rcp_f32_e32 v10, v10
	v_add_f32_e32 v11, 1.0, v11
	v_rcp_f32_e32 v11, v11
	v_mul_f32_e32 v10, v10, v16
	v_cvt_pk_bf16_f32 v250, v0, v10
	v_add_f32_e32 v0, v12, v22
	v_mul_f32_e32 v0, 0xbfb8aa3b, v0
	v_exp_f32_e32 v0, v0
	v_mul_f32_e32 v11, v11, v17
	v_add_f32_e32 v0, 1.0, v0
	v_rcp_f32_e32 v0, v0
	s_nop 0
	v_mul_f32_e32 v0, v0, v24
	v_cvt_pk_bf16_f32 v251, v0, v11
	v_lshl_add_u64 v[252:253], v[14:15], 0, v[176:177]
	s_nop 1
	v_permlane16_swap_b32_e32 v248, v250
	v_permlane16_swap_b32_e32 v249, v251
	global_store_dwordx4 v[252:253], v[248:251], off
	s_waitcnt vmcnt(8)
	v_mov_b64_e32 v[16:17], v[146:147]
	ds_read_b128 v[10:13], v172 offset:128
	v_lshlrev_b32_e32 v0, 16, v16
	s_waitcnt lgkmcnt(0)
	v_add_f32_e32 v6, v6, v10
	v_mul_f32_e32 v6, 0xbfb8aa3b, v6
	v_exp_f32_e32 v6, v6
	v_and_b32_e32 v16, 0xffff0000, v16
	v_lshlrev_b32_e32 v20, 16, v17
	v_and_b32_e32 v17, 0xffff0000, v17
	v_add_f32_e32 v6, 1.0, v6
	v_rcp_f32_e32 v6, v6
	s_nop 0
	v_mul_f32_e32 v0, v6, v0
	v_add_f32_e32 v6, v7, v11
	v_mul_f32_e32 v6, 0xbfb8aa3b, v6
	v_exp_f32_e32 v6, v6
	v_add_f32_e32 v7, v9, v13
	v_mul_f32_e32 v7, 0xbfb8aa3b, v7
	v_exp_f32_e32 v7, v7
	v_add_f32_e32 v6, 1.0, v6
	v_rcp_f32_e32 v6, v6
	v_add_f32_e32 v7, 1.0, v7
	v_rcp_f32_e32 v7, v7
	v_mul_f32_e32 v6, v6, v16
	v_cvt_pk_bf16_f32 v248, v0, v6
	v_add_f32_e32 v0, v8, v12
	v_mul_f32_e32 v0, 0xbfb8aa3b, v0
	v_exp_f32_e32 v0, v0
	v_mul_f32_e32 v7, v7, v17
	v_add_f32_e32 v0, 1.0, v0
	v_rcp_f32_e32 v0, v0
	s_nop 0
	v_mul_f32_e32 v0, v0, v20
	v_cvt_pk_bf16_f32 v249, v0, v7
	s_waitcnt vmcnt(7)
	v_mov_b64_e32 v[6:7], v[148:149]
	ds_read_b128 v[8:11], v172 offset:192
	v_lshlrev_b32_e32 v0, 16, v6
	s_waitcnt lgkmcnt(0)
	v_add_f32_e32 v2, v2, v8
	v_mul_f32_e32 v2, 0xbfb8aa3b, v2
	v_exp_f32_e32 v2, v2
	v_and_b32_e32 v6, 0xffff0000, v6
	v_lshlrev_b32_e32 v12, 16, v7
	v_and_b32_e32 v7, 0xffff0000, v7
	v_add_f32_e32 v2, 1.0, v2
	v_rcp_f32_e32 v2, v2
	s_nop 0
	v_mul_f32_e32 v0, v2, v0
	v_add_f32_e32 v2, v3, v9
	v_mul_f32_e32 v2, 0xbfb8aa3b, v2
	v_exp_f32_e32 v2, v2
	v_add_f32_e32 v3, v5, v11
	v_mul_f32_e32 v3, 0xbfb8aa3b, v3
	v_exp_f32_e32 v3, v3
	v_add_f32_e32 v2, 1.0, v2
	v_rcp_f32_e32 v2, v2
	v_add_f32_e32 v3, 1.0, v3
	v_rcp_f32_e32 v3, v3
	v_mul_f32_e32 v2, v2, v6
	v_cvt_pk_bf16_f32 v250, v0, v2
	v_add_f32_e32 v0, v4, v10
	v_mul_f32_e32 v0, 0xbfb8aa3b, v0
	v_exp_f32_e32 v0, v0
	v_mul_f32_e32 v3, v3, v7
	v_add_f32_e32 v0, 1.0, v0
	v_rcp_f32_e32 v0, v0
	s_nop 0
	v_mul_f32_e32 v0, v0, v12
	v_cvt_pk_bf16_f32 v251, v0, v3
	v_lshl_add_u64 v[252:253], v[14:15], 0, v[176:177]
	s_nop 1
	v_permlane16_swap_b32_e32 v248, v250
	v_permlane16_swap_b32_e32 v249, v251
	global_store_dwordx4 v[252:253], v[248:251], off offset:64
	s_andn2_b64 vcc, exec, s[18:19]
	s_mov_b64 s[18:19], -1
	s_cbranch_vccnz .LBB0_1384
	s_mov_b64 s[18:19], 0
	s_branch .LBB0_1384
